# hbkeep12: 12 of 16 bf16 h blocks kept on-chip from P3 to P4 (11 in VGPRs, 1 in the unused LDS tail above the GEMM stages)
# speedup vs baseline: 1.0100x; 1.0016x over previous
; __device__ __forceinline__ unsigned cvtpk(float lo, float hi) { f32x2 v = {lo, hi}; bf16x2_t b = __builtin_convertvector(v, bf16x2_t); return __builtin_bit_cast(unsigned, b); }
;     __device__ __forceinline__ void operator()(const Acc& acc, const Unit& u, int wr, int wc, int fr, int fq) const {
;     ...
;             for (int m = 0; m < 4; ++m) { const size_t off = (size_t)(u.pm * 256 + ai * 128 + wr * 64 + m * 16 + fr) * DM + colbase;
; #pragma unroll
;                 for (int bj = 0; bj < 2; ++bj) { xv[m][bj][0] = __builtin_nontemporal_load((const f32x4*)(x + off + 32 * bj)); xv[m][bj][1] = __builtin_nontemporal_load((const f32x4*)(x + off + 32 * bj + 4)); } }
; #pragma unroll
;             for (int m = 0; m < 4; ++m) {
;                 const int row = u.pm * 256 + ai * 128 + wr * 64 + m * 16 + fr;
;                 float ss = 0.f;
; #pragma unroll
;                 for (int bj = 0; bj < 2; ++bj) {
;                     const size_t off = (size_t)row * DM + colbase + 32 * bj;
;                     const f32x4 h0 = xv[m][bj][0] + acc[ai][bj][m][0], h1 = xv[m][bj][1] + acc[ai][bj][m][1];
;                     u32x4 w; w.x = cvtpk(h0.x, h0.y); w.y = cvtpk(h0.z, h0.w); w.z = cvtpk(h1.x, h1.y); w.w = cvtpk(h1.z, h1.w);
;                     *(u32x4*)(HB + off) = w;
;                     ss += (h0.x * h0.x + h0.y * h0.y) + (h0.z * h0.z + h0.w * h0.w) + (h1.x * h1.x + h1.y * h1.y) + (h1.z * h1.z + h1.w * h1.w);
;                 }
;                 ss = quad_sum(ss);
;                 if (fq == 0) atomicAdd(rowss + row, ss);
.LBB0_735:
	s_or_b64 exec, exec, s[20:21]
	v_lshlrev_b64 v[48:49], 12, v[118:119]
	v_pk_add_f32 v[46:47], v[46:47], v[110:111]
	v_pk_add_f32 v[44:45], v[44:45], v[108:109]
	v_pk_add_f32 v[50:51], v[42:43], v[106:107]
	v_pk_add_f32 v[52:53], v[40:41], v[104:105]
	v_lshl_add_u64 v[48:49], s[10:11], 0, v[48:49]
	v_cvt_pk_bf16_f32 v40, v44, v45
	v_cvt_pk_bf16_f32 v41, v46, v47
	v_cvt_pk_bf16_f32 v42, v52, v53
	v_cvt_pk_bf16_f32 v43, v50, v51
	v_lshl_add_u64 v[48:49], v[188:189], 1, v[48:49]
	v_mov_b64_e32 v[222:223], v[40:41]
	v_mov_b64_e32 v[250:251], v[42:43]
	flat_store_dwordx4 v[48:49], v[40:43]
	v_pk_add_f32 v[36:37], v[36:37], v[100:101]
	v_pk_add_f32 v[38:39], v[38:39], v[102:103]
	v_mul_f32_e32 v40, v45, v45
	v_mul_f32_e32 v41, v47, v47
	v_fmac_f32_e32 v40, v44, v44
	v_fmac_f32_e32 v41, v46, v46
	v_add_f32_e32 v40, v40, v41
	v_mul_f32_e32 v41, v53, v53
	v_fmac_f32_e32 v41, v52, v52
	v_add_f32_e32 v40, v40, v41
	v_mul_f32_e32 v41, v51, v51
	v_fmac_f32_e32 v41, v50, v50
	v_add_f32_e32 v42, v41, v40
	v_pk_add_f32 v[40:41], v[34:35], v[98:99]
	v_pk_add_f32 v[34:35], v[32:33], v[96:97]
	v_mul_f32_e32 v33, v37, v37
	v_cvt_pk_bf16_f32 v32, v36, v37
	v_fmac_f32_e32 v33, v36, v36
	v_mul_f32_e32 v36, v39, v39
	v_fmac_f32_e32 v36, v38, v38
	v_add_f32_e32 v33, v33, v36
	v_mul_f32_e32 v36, v35, v35
	v_fmac_f32_e32 v36, v34, v34
	v_add_f32_e32 v33, v33, v36
	v_mul_f32_e32 v36, v41, v41
	v_fmac_f32_e32 v36, v40, v40
	v_add_f32_e32 v33, v36, v33
	v_add_f32_e32 v36, v42, v33
	ds_swizzle_b32 v37, v36 offset:swizzle(SWAP,16)
	v_cvt_pk_bf16_f32 v33, v38, v39
	v_cvt_pk_bf16_f32 v34, v34, v35
	v_cvt_pk_bf16_f32 v35, v40, v41
	v_mov_b32_e32 v206, 0x20000
	v_lshl_add_u32 v206, v200, 4, v206
	v_lshl_add_u32 v206, s79, 6, v206
	v_lshl_add_u32 v206, s86, 4, v206
	ds_write_b128 v206, v[32:35]
	flat_store_dwordx4 v[48:49], v[32:35] offset:64
	s_waitcnt lgkmcnt(0)
	s_nop 0
	v_add_f32_e32 v32, v36, v37
	v_mov_b32_e32 v33, v32
	s_nop 1
	v_permlane32_swap_b32_e32 v32, v33
	s_and_saveexec_b64 s[20:21], vcc
	s_cbranch_execz .LBB0_737
	v_add_f32_e32 v32, v32, v33
	flat_atomic_add_f32 v[112:113], v32 offset:576

; __device__ __forceinline__ float bflo(unsigned u) { return __uint_as_float(u << 16); }
;     __device__ __forceinline__ void operator()(const Acc& acc, const Unit& u, int wr, int wc, int fr, int fq) const {
;     ...
;             for (int m = 0; m < 4; ++m) { const int row = u.pm * 256 + ai * 128 + wr * 64 + m * 16 + fr; const size_t off = (size_t)row * DM + colbase;
;                 rsv[m] = rowss[row];
; #pragma unroll
;                 for (int bj = 0; bj < 2; ++bj) { const u32x4 hw = __builtin_nontemporal_load((const u32x4*)(hin + off + 32 * bj));
;                     hv[m][bj][0] = (f32x4){bflo(hw.x), bfhi(hw.x), bflo(hw.y), bfhi(hw.y)}; hv[m][bj][1] = (f32x4){bflo(hw.z), bfhi(hw.z), bflo(hw.w), bfhi(hw.w)};
;                     pw[m][bj] = __builtin_nontemporal_load((const u32x4*)(PP + off + 32 * bj)); } }
; #pragma unroll
;             for (int m = 0; m < 4; ++m) {
;                 const int row = u.pm * 256 + ai * 128 + wr * 64 + m * 16 + fr;
;                 const float rs = rsqrtf(rsv[m] * (1.0f / DM) + EPS) * -1.4426950408889634f;
; #pragma unroll
;                 for (int bj = 0; bj < 2; ++bj) {
;                     const size_t off = (size_t)row * DM + colbase + 32 * bj;
;                     f32x4 h0 = hv[m][bj][0], h1 = hv[m][bj][1];
;                     const u32x4 p4 = pw[m][bj];
;                     const f32x4 a0 = acc[ai][bj][m][0], a1 = acc[ai][bj][m][1];
;                     h0.x += bflo(p4.x) * __builtin_amdgcn_rcpf(1.0f + __builtin_amdgcn_exp2f(a0.x * rs));
;                     h0.y += bfhi(p4.x) * __builtin_amdgcn_rcpf(1.0f + __builtin_amdgcn_exp2f(a0.y * rs));
;                     h0.z += bflo(p4.y) * __builtin_amdgcn_rcpf(1.0f + __builtin_amdgcn_exp2f(a0.z * rs));
;                     h0.w += bfhi(p4.y) * __builtin_amdgcn_rcpf(1.0f + __builtin_amdgcn_exp2f(a0.w * rs));
;                     h1.x += bflo(p4.z) * __builtin_amdgcn_rcpf(1.0f + __builtin_amdgcn_exp2f(a1.x * rs));
;                     h1.y += bfhi(p4.z) * __builtin_amdgcn_rcpf(1.0f + __builtin_amdgcn_exp2f(a1.y * rs));
;                     h1.z += bflo(p4.w) * __builtin_amdgcn_rcpf(1.0f + __builtin_amdgcn_exp2f(a1.z * rs));
;                     h1.w += bfhi(p4.w) * __builtin_amdgcn_rcpf(1.0f + __builtin_amdgcn_exp2f(a1.w * rs));
;                     *(f32x4*)(out + off) = h0; *(f32x4*)(out + off + 4) = h1;
.LBB0_814:
	v_mov_b64_e32 v[206:207], v[224:225]
	v_mov_b64_e32 v[208:209], v[226:227]
	v_mov_b64_e32 v[172:173], v[228:229]
	v_mov_b64_e32 v[174:175], v[230:231]
	v_mov_b64_e32 v[164:165], v[232:233]
	v_mov_b64_e32 v[166:167], v[234:235]
	v_mov_b64_e32 v[156:157], v[236:237]
	v_mov_b64_e32 v[158:159], v[238:239]
	v_mov_b64_e32 v[148:149], v[240:241]
	v_mov_b64_e32 v[150:151], v[242:243]
	v_mov_b64_e32 v[140:141], v[210:211]
	v_mov_b64_e32 v[142:143], v[212:213]
	v_mov_b64_e32 v[236:237], v[218:219]
	v_mov_b64_e32 v[238:239], v[220:221]
	v_mov_b64_e32 v[240:241], v[222:223]
	v_mov_b32_e32 v128, v200
	s_lshl_b32 s11, s42, 8
	v_and_b32_e32 v129, 15, v128
	v_bfe_u32 v128, v128, 4, 2
	s_or_b32 s11, s11, s86
	s_nop 0
	v_lshl_add_u32 v188, v128, 3, s11
	s_lshl_b32 s11, s41, 8
	s_add_i32 s11, s11, s79
	v_add_u32_e32 v190, s11, v129
	v_ashrrev_i32_e32 v191, 31, v190
	v_lshl_add_u64 v[192:193], v[190:191], 2, s[80:81]
	flat_load_dword v226, v[192:193]
	v_ashrrev_i32_e32 v189, 31, v188
	v_lshlrev_b64 v[128:129], 11, v[190:191]
	v_lshl_add_u64 v[222:223], v[128:129], 0, v[188:189]
	v_lshlrev_b64 v[128:129], 1, v[222:223]
	v_lshl_add_u64 v[130:131], s[6:7], 0, v[128:129]
	v_lshl_add_u64 v[128:129], s[8:9], 0, v[128:129]
	flat_load_dwordx4 v[210:213], v[128:129] nt
	flat_load_dword v234, v[192:193] offset:64
	flat_load_dword v235, v[192:193] offset:128
	flat_load_dword v191, v[192:193] offset:192
	flat_load_dwordx4 v[218:221], v[128:129] offset:64 nt
	v_add_u32_e32 v132, 16, v190
	v_add_u32_e32 v134, 32, v190
	v_add_u32_e32 v136, 48, v190
	v_ashrrev_i32_e32 v133, 31, v132
	v_ashrrev_i32_e32 v135, 31, v134
	v_ashrrev_i32_e32 v137, 31, v136
	v_lshlrev_b64 v[132:133], 11, v[132:133]
	v_lshlrev_b64 v[134:135], 11, v[134:135]
	v_lshlrev_b64 v[136:137], 11, v[136:137]
	v_lshl_add_u64 v[198:199], v[132:133], 0, v[188:189]
	v_lshl_add_u64 v[196:197], v[134:135], 0, v[188:189]
	v_lshl_add_u64 v[194:195], v[136:137], 0, v[188:189]
	v_lshlrev_b64 v[132:133], 1, v[198:199]
	v_lshlrev_b64 v[134:135], 1, v[196:197]
	v_lshlrev_b64 v[136:137], 1, v[194:195]
	v_lshl_add_u64 v[128:129], s[6:7], 0, v[132:133]
	v_lshl_add_u64 v[130:131], s[8:9], 0, v[132:133]
	v_lshl_add_u64 v[132:133], s[6:7], 0, v[134:135]
	v_lshl_add_u64 v[134:135], s[8:9], 0, v[134:135]
	v_lshl_add_u64 v[138:139], s[6:7], 0, v[136:137]
	v_lshl_add_u64 v[224:225], s[8:9], 0, v[136:137]
	flat_load_dwordx4 v[168:171], v[130:131] nt
	flat_load_dwordx4 v[160:163], v[130:131] offset:64 nt
	flat_load_dwordx4 v[152:155], v[134:135] nt
	flat_load_dwordx4 v[144:147], v[134:135] offset:64 nt
	s_nop 0
	v_mov_b64_e32 v[132:133], v[244:245]
	v_mov_b64_e32 v[134:135], v[246:247]
	s_nop 0
	flat_load_dwordx4 v[136:139], v[224:225] nt
	flat_load_dwordx4 v[128:131], v[224:225] offset:64 nt
	s_waitcnt vmcnt(0) lgkmcnt(0)
	v_fmamk_f32 v224, v226, 0x3a000000, v205
	v_mul_f32_e32 v225, 0x4b800000, v224
	v_cmp_gt_f32_e32 vcc, s40, v224
	v_lshlrev_b32_e32 v228, 16, v208
	s_nop 0
	v_cndmask_b32_e32 v224, v224, v225, vcc
	v_rsq_f32_e32 v232, v224
	v_and_b32_e32 v229, 0xffff0000, v208
	v_lshlrev_b32_e32 v230, 16, v212
	v_and_b32_e32 v231, 0xffff0000, v212
	v_mul_f32_e32 v208, 0x45800000, v232
	v_cndmask_b32_e32 v208, v232, v208, vcc
	v_mul_f32_e32 v212, 0xbfb8aa3b, v208
	v_mul_f32_e32 v124, v124, v212
	v_mul_f32_e32 v125, v125, v212
	v_mul_f32_e32 v120, v120, v212
	v_mul_f32_e32 v121, v121, v212
	v_exp_f32_e32 v124, v124
	v_exp_f32_e32 v125, v125
	v_exp_f32_e32 v120, v120
	v_exp_f32_e32 v121, v121
	v_add_f32_e32 v124, 1.0, v124
	v_add_f32_e32 v125, 1.0, v125
	v_add_f32_e32 v208, 1.0, v120
	v_add_f32_e32 v233, 1.0, v121
	v_rcp_f32_e32 v120, v124
	v_rcp_f32_e32 v121, v125
	v_lshlrev_b32_e32 v224, 16, v206
	v_and_b32_e32 v225, 0xffff0000, v206
	v_lshlrev_b32_e32 v226, 16, v210
	v_and_b32_e32 v227, 0xffff0000, v210
	v_mul_f32_e32 v126, v126, v212
	v_mul_f32_e32 v127, v127, v212
	v_mul_f32_e32 v122, v122, v212
	v_exp_f32_e32 v126, v126
	v_exp_f32_e32 v127, v127
	v_pk_fma_f32 v[124:125], v[120:121], v[226:227], v[224:225]
	v_mul_f32_e32 v120, v123, v212
	v_exp_f32_e32 v122, v122
	v_exp_f32_e32 v123, v120
	v_mul_f32_e32 v116, v116, v212
	v_mul_f32_e32 v117, v117, v212
	v_exp_f32_e32 v116, v116
	v_exp_f32_e32 v117, v117
	v_mul_f32_e32 v118, v118, v212
	v_mul_f32_e32 v119, v119, v212
	v_add_f32_e32 v126, 1.0, v126
	v_add_f32_e32 v127, 1.0, v127
	v_exp_f32_e32 v118, v118
	v_exp_f32_e32 v119, v119
	v_mul_f32_e32 v112, v112, v212
	v_mul_f32_e32 v113, v113, v212
	v_rcp_f32_e32 v126, v126
	v_rcp_f32_e32 v127, v127
	v_add_f32_e32 v122, 1.0, v122
	v_add_f32_e32 v123, 1.0, v123
	v_exp_f32_e32 v112, v112
	v_exp_f32_e32 v113, v113
	v_rcp_f32_e32 v232, v208
	v_rcp_f32_e32 v233, v233
	v_rcp_f32_e32 v122, v122
	v_rcp_f32_e32 v123, v123
	v_add_f32_e32 v116, 1.0, v116
	v_add_f32_e32 v117, 1.0, v117
	v_lshlrev_b32_e32 v206, 16, v207
	v_and_b32_e32 v207, 0xffff0000, v207
	v_lshlrev_b32_e32 v210, 16, v211
	v_and_b32_e32 v211, 0xffff0000, v211
	v_rcp_f32_e32 v116, v116
	v_rcp_f32_e32 v117, v117
	v_add_f32_e32 v118, 1.0, v118
	v_add_f32_e32 v119, 1.0, v119
	v_pk_fma_f32 v[126:127], v[126:127], v[210:211], v[206:207]
	v_lshlrev_b32_e32 v206, 16, v209
	v_and_b32_e32 v207, 0xffff0000, v209
	v_lshlrev_b32_e32 v208, 16, v213
	v_and_b32_e32 v209, 0xffff0000, v213
	v_rcp_f32_e32 v118, v118
	v_rcp_f32_e32 v119, v119
	v_add_f32_e32 v112, 1.0, v112
	v_add_f32_e32 v113, 1.0, v113
	v_pk_fma_f32 v[120:121], v[232:233], v[230:231], v[228:229]
	v_pk_fma_f32 v[122:123], v[122:123], v[208:209], v[206:207]
	v_lshl_add_u64 v[206:207], v[222:223], 2, s[2:3]
	v_rcp_f32_e32 v112, v112
	v_rcp_f32_e32 v113, v113
	flat_store_dwordx4 v[206:207], v[120:123] offset:16
; __device__ __forceinline__ float bflo(unsigned u) { return __uint_as_float(u << 16); }
; __device__ __forceinline__ float bfhi(unsigned u) { return __uint_as_float(u & 0xffff0000u); }
;     __device__ __forceinline__ void operator()(const Acc& acc, const Unit& u, int wr, int wc, int fr, int fq) const {
;     ...
;             for (int m = 0; m < 4; ++m) {
;                 const int row = u.pm * 256 + ai * 128 + wr * 64 + m * 16 + fr;
;                 const float rs = rsqrtf(rsv[m] * (1.0f / DM) + EPS) * -1.4426950408889634f;
; #pragma unroll
;                 for (int bj = 0; bj < 2; ++bj) {
;                     const size_t off = (size_t)row * DM + colbase + 32 * bj;
;                     f32x4 h0 = hv[m][bj][0], h1 = hv[m][bj][1];
;                     const u32x4 p4 = pw[m][bj];
;                     const f32x4 a0 = acc[ai][bj][m][0], a1 = acc[ai][bj][m][1];
;                     h0.x += bflo(p4.x) * __builtin_amdgcn_rcpf(1.0f + __builtin_amdgcn_exp2f(a0.x * rs));
;                     h0.y += bfhi(p4.x) * __builtin_amdgcn_rcpf(1.0f + __builtin_amdgcn_exp2f(a0.y * rs));
;                     h0.z += bflo(p4.y) * __builtin_amdgcn_rcpf(1.0f + __builtin_amdgcn_exp2f(a0.z * rs));
;                     h0.w += bfhi(p4.y) * __builtin_amdgcn_rcpf(1.0f + __builtin_amdgcn_exp2f(a0.w * rs));
;                     h1.x += bflo(p4.z) * __builtin_amdgcn_rcpf(1.0f + __builtin_amdgcn_exp2f(a1.x * rs));
;                     h1.y += bfhi(p4.z) * __builtin_amdgcn_rcpf(1.0f + __builtin_amdgcn_exp2f(a1.y * rs));
;                     h1.z += bflo(p4.w) * __builtin_amdgcn_rcpf(1.0f + __builtin_amdgcn_exp2f(a1.z * rs));
;                     h1.w += bfhi(p4.w) * __builtin_amdgcn_rcpf(1.0f + __builtin_amdgcn_exp2f(a1.w * rs));
;                     *(f32x4*)(out + off) = h0; *(f32x4*)(out + off + 4) = h1;
	flat_store_dwordx4 v[206:207], v[124:127]
	v_mul_f32_e32 v114, v114, v212
	v_lshlrev_b32_e32 v120, 16, v214
	v_and_b32_e32 v121, 0xffff0000, v214
	v_lshlrev_b32_e32 v122, 16, v218
	v_and_b32_e32 v123, 0xffff0000, v218
	v_pk_fma_f32 v[116:117], v[116:117], v[122:123], v[120:121]
	v_lshlrev_b32_e32 v120, 16, v215
	v_and_b32_e32 v121, 0xffff0000, v215
	v_lshlrev_b32_e32 v122, 16, v219
	v_and_b32_e32 v123, 0xffff0000, v219
	v_pk_fma_f32 v[118:119], v[118:119], v[122:123], v[120:121]
	v_lshlrev_b32_e32 v120, 16, v216
	v_and_b32_e32 v121, 0xffff0000, v216
	v_lshlrev_b32_e32 v122, 16, v220
	v_and_b32_e32 v123, 0xffff0000, v220
	v_pk_fma_f32 v[112:113], v[112:113], v[122:123], v[120:121]
	v_fmamk_f32 v123, v234, 0x3a000000, v205
	v_mul_f32_e32 v124, 0x4b800000, v123
	v_cmp_gt_f32_e32 vcc, s40, v123
	flat_store_dwordx4 v[206:207], v[116:119] offset:128
	v_mul_f32_e32 v115, v115, v212
	v_cndmask_b32_e32 v123, v123, v124, vcc
	v_rsq_f32_e32 v124, v123
	v_exp_f32_e32 v114, v114
	v_exp_f32_e32 v115, v115
	v_lshlrev_b32_e32 v120, 16, v217
	v_mul_f32_e32 v116, 0x45800000, v124
	v_cndmask_b32_e32 v116, v124, v116, vcc
	v_mul_f32_e32 v116, 0xbfb8aa3b, v116
	v_mul_f32_e32 v108, v108, v116
	v_mul_f32_e32 v109, v109, v116
	v_exp_f32_e32 v108, v108
	v_exp_f32_e32 v109, v109
	v_mul_f32_e32 v110, v110, v116
	v_mul_f32_e32 v111, v111, v116
	v_exp_f32_e32 v110, v110
	v_exp_f32_e32 v111, v111
	v_mul_f32_e32 v104, v104, v116
	v_mul_f32_e32 v105, v105, v116
	v_add_f32_e32 v114, 1.0, v114
	v_add_f32_e32 v115, 1.0, v115
	v_exp_f32_e32 v104, v104
	v_exp_f32_e32 v105, v105
	v_mul_f32_e32 v106, v106, v116
	v_mul_f32_e32 v107, v107, v116
	v_rcp_f32_e32 v114, v114
	v_rcp_f32_e32 v115, v115
	v_exp_f32_e32 v106, v106
	v_exp_f32_e32 v107, v107
	v_add_f32_e32 v108, 1.0, v108
	v_add_f32_e32 v109, 1.0, v109
	v_mul_f32_e32 v100, v100, v116
	v_mul_f32_e32 v101, v101, v116
	v_rcp_f32_e32 v108, v108
	v_rcp_f32_e32 v109, v109
	v_add_f32_e32 v110, 1.0, v110
	v_add_f32_e32 v111, 1.0, v111
	v_exp_f32_e32 v100, v100
	v_exp_f32_e32 v101, v101
	v_mul_f32_e32 v102, v102, v116
	v_mul_f32_e32 v103, v103, v116
	v_and_b32_e32 v121, 0xffff0000, v217
	v_lshlrev_b32_e32 v122, 16, v221
	v_and_b32_e32 v123, 0xffff0000, v221
	v_rcp_f32_e32 v110, v110
	v_rcp_f32_e32 v111, v111
	v_add_f32_e32 v104, 1.0, v104
	v_add_f32_e32 v105, 1.0, v105
	v_exp_f32_e32 v102, v102
	v_exp_f32_e32 v103, v103
	v_mul_f32_e32 v96, v96, v116
	v_mul_f32_e32 v97, v97, v116
	v_pk_fma_f32 v[114:115], v[114:115], v[122:123], v[120:121]
	v_rcp_f32_e32 v104, v104
	v_rcp_f32_e32 v105, v105
	v_add_f32_e32 v106, 1.0, v106
	v_add_f32_e32 v107, 1.0, v107
	v_exp_f32_e32 v96, v96
	v_exp_f32_e32 v97, v97
	flat_store_dwordx4 v[206:207], v[112:115] offset:144
	v_rcp_f32_e32 v106, v106
	v_rcp_f32_e32 v107, v107
	v_lshlrev_b32_e32 v112, 16, v172
	v_and_b32_e32 v113, 0xffff0000, v172
	v_lshlrev_b32_e32 v114, 16, v168
	v_and_b32_e32 v115, 0xffff0000, v168
	v_pk_fma_f32 v[108:109], v[108:109], v[114:115], v[112:113]
	v_lshlrev_b32_e32 v112, 16, v173
	v_and_b32_e32 v113, 0xffff0000, v173
	v_lshlrev_b32_e32 v114, 16, v169
	v_and_b32_e32 v115, 0xffff0000, v169
	v_add_f32_e32 v100, 1.0, v100
	v_add_f32_e32 v101, 1.0, v101
	v_pk_fma_f32 v[110:111], v[110:111], v[114:115], v[112:113]
	v_lshlrev_b32_e32 v112, 16, v174
	v_and_b32_e32 v113, 0xffff0000, v174
	v_lshlrev_b32_e32 v114, 16, v170
	v_and_b32_e32 v115, 0xffff0000, v170
	v_rcp_f32_e32 v100, v100
	v_rcp_f32_e32 v101, v101
	v_add_f32_e32 v102, 1.0, v102
	v_add_f32_e32 v103, 1.0, v103
	v_pk_fma_f32 v[104:105], v[104:105], v[114:115], v[112:113]
	v_lshlrev_b32_e32 v112, 16, v175
	v_and_b32_e32 v113, 0xffff0000, v175
	v_lshlrev_b32_e32 v114, 16, v171
	v_and_b32_e32 v115, 0xffff0000, v171
	v_rcp_f32_e32 v102, v102
	v_rcp_f32_e32 v103, v103
	v_add_f32_e32 v96, 1.0, v96
	v_add_f32_e32 v97, 1.0, v97
	v_pk_fma_f32 v[106:107], v[106:107], v[114:115], v[112:113]
	v_lshl_add_u64 v[112:113], v[198:199], 2, s[2:3]
	v_rcp_f32_e32 v96, v96
	v_rcp_f32_e32 v97, v97
	flat_store_dwordx4 v[112:113], v[104:107] offset:16
	flat_store_dwordx4 v[112:113], v[108:111]
	v_mul_f32_e32 v98, v98, v116
	v_lshlrev_b32_e32 v104, 16, v164
	v_and_b32_e32 v105, 0xffff0000, v164
	v_lshlrev_b32_e32 v106, 16, v160
	v_and_b32_e32 v107, 0xffff0000, v160
	v_pk_fma_f32 v[100:101], v[100:101], v[106:107], v[104:105]
	v_lshlrev_b32_e32 v104, 16, v165
	v_and_b32_e32 v105, 0xffff0000, v165
	v_lshlrev_b32_e32 v106, 16, v161
	v_and_b32_e32 v107, 0xffff0000, v161
	v_pk_fma_f32 v[102:103], v[102:103], v[106:107], v[104:105]
	v_lshlrev_b32_e32 v104, 16, v166
	v_and_b32_e32 v105, 0xffff0000, v166
	v_lshlrev_b32_e32 v106, 16, v162
	v_and_b32_e32 v107, 0xffff0000, v162
	v_pk_fma_f32 v[96:97], v[96:97], v[106:107], v[104:105]
	v_fmamk_f32 v107, v235, 0x3a000000, v205
	v_mul_f32_e32 v108, 0x4b800000, v107
	v_cmp_gt_f32_e32 vcc, s40, v107
	flat_store_dwordx4 v[112:113], v[100:103] offset:128
	v_mul_f32_e32 v99, v99, v116
	v_cndmask_b32_e32 v107, v107, v108, vcc
	v_rsq_f32_e32 v108, v107
	v_exp_f32_e32 v98, v98
	v_exp_f32_e32 v99, v99
	v_lshlrev_b32_e32 v104, 16, v167
	v_mul_f32_e32 v100, 0x45800000, v108
	v_cndmask_b32_e32 v100, v108, v100, vcc
	v_mul_f32_e32 v100, 0xbfb8aa3b, v100
	v_mul_f32_e32 v92, v92, v100
	v_mul_f32_e32 v93, v93, v100
	v_exp_f32_e32 v92, v92
	v_exp_f32_e32 v93, v93
	v_mul_f32_e32 v94, v94, v100
	v_mul_f32_e32 v95, v95, v100
	v_exp_f32_e32 v94, v94
	v_exp_f32_e32 v95, v95
	v_mul_f32_e32 v88, v88, v100
	v_mul_f32_e32 v89, v89, v100
	v_add_f32_e32 v98, 1.0, v98
	v_add_f32_e32 v99, 1.0, v99
	v_exp_f32_e32 v88, v88
	v_exp_f32_e32 v89, v89
	v_mul_f32_e32 v90, v90, v100
	v_mul_f32_e32 v91, v91, v100
	v_rcp_f32_e32 v98, v98
; __device__ __forceinline__ float bflo(unsigned u) { return __uint_as_float(u << 16); }
; __device__ __forceinline__ float bfhi(unsigned u) { return __uint_as_float(u & 0xffff0000u); }
;     __device__ __forceinline__ void operator()(const Acc& acc, const Unit& u, int wr, int wc, int fr, int fq) const {
;     ...
;             for (int m = 0; m < 4; ++m) {
;                 const int row = u.pm * 256 + ai * 128 + wr * 64 + m * 16 + fr;
;                 const float rs = rsqrtf(rsv[m] * (1.0f / DM) + EPS) * -1.4426950408889634f;
; #pragma unroll
;                 for (int bj = 0; bj < 2; ++bj) {
;                     const size_t off = (size_t)row * DM + colbase + 32 * bj;
;                     f32x4 h0 = hv[m][bj][0], h1 = hv[m][bj][1];
;                     const u32x4 p4 = pw[m][bj];
;                     const f32x4 a0 = acc[ai][bj][m][0], a1 = acc[ai][bj][m][1];
;                     h0.x += bflo(p4.x) * __builtin_amdgcn_rcpf(1.0f + __builtin_amdgcn_exp2f(a0.x * rs));
;                     h0.y += bfhi(p4.x) * __builtin_amdgcn_rcpf(1.0f + __builtin_amdgcn_exp2f(a0.y * rs));
;                     h0.z += bflo(p4.y) * __builtin_amdgcn_rcpf(1.0f + __builtin_amdgcn_exp2f(a0.z * rs));
;                     h0.w += bfhi(p4.y) * __builtin_amdgcn_rcpf(1.0f + __builtin_amdgcn_exp2f(a0.w * rs));
;                     h1.x += bflo(p4.z) * __builtin_amdgcn_rcpf(1.0f + __builtin_amdgcn_exp2f(a1.x * rs));
;                     h1.y += bfhi(p4.z) * __builtin_amdgcn_rcpf(1.0f + __builtin_amdgcn_exp2f(a1.y * rs));
;                     h1.z += bflo(p4.w) * __builtin_amdgcn_rcpf(1.0f + __builtin_amdgcn_exp2f(a1.z * rs));
;                     h1.w += bfhi(p4.w) * __builtin_amdgcn_rcpf(1.0f + __builtin_amdgcn_exp2f(a1.w * rs));
;                     *(f32x4*)(out + off) = h0; *(f32x4*)(out + off + 4) = h1;
	v_rcp_f32_e32 v99, v99
	v_exp_f32_e32 v90, v90
	v_exp_f32_e32 v91, v91
	v_add_f32_e32 v92, 1.0, v92
	v_add_f32_e32 v93, 1.0, v93
	v_mul_f32_e32 v84, v84, v100
	v_mul_f32_e32 v85, v85, v100
	v_rcp_f32_e32 v92, v92
	v_rcp_f32_e32 v93, v93
	v_add_f32_e32 v94, 1.0, v94
	v_add_f32_e32 v95, 1.0, v95
	v_exp_f32_e32 v84, v84
	v_exp_f32_e32 v85, v85
	v_mul_f32_e32 v86, v86, v100
	v_mul_f32_e32 v87, v87, v100
	v_and_b32_e32 v105, 0xffff0000, v167
	v_lshlrev_b32_e32 v106, 16, v163
	v_and_b32_e32 v107, 0xffff0000, v163
	v_rcp_f32_e32 v94, v94
	v_rcp_f32_e32 v95, v95
	v_add_f32_e32 v88, 1.0, v88
	v_add_f32_e32 v89, 1.0, v89
	v_exp_f32_e32 v86, v86
	v_exp_f32_e32 v87, v87
	v_mul_f32_e32 v80, v80, v100
	v_mul_f32_e32 v81, v81, v100
	v_pk_fma_f32 v[98:99], v[98:99], v[106:107], v[104:105]
	v_rcp_f32_e32 v88, v88
	v_rcp_f32_e32 v89, v89
	v_add_f32_e32 v90, 1.0, v90
	v_add_f32_e32 v91, 1.0, v91
	v_exp_f32_e32 v80, v80
	v_exp_f32_e32 v81, v81
	flat_store_dwordx4 v[112:113], v[96:99] offset:144
	v_rcp_f32_e32 v90, v90
	v_rcp_f32_e32 v91, v91
	v_lshlrev_b32_e32 v96, 16, v156
	v_and_b32_e32 v97, 0xffff0000, v156
	v_lshlrev_b32_e32 v98, 16, v152
	v_and_b32_e32 v99, 0xffff0000, v152
	v_pk_fma_f32 v[92:93], v[92:93], v[98:99], v[96:97]
	v_lshlrev_b32_e32 v96, 16, v157
	v_and_b32_e32 v97, 0xffff0000, v157
	v_lshlrev_b32_e32 v98, 16, v153
	v_and_b32_e32 v99, 0xffff0000, v153
	v_add_f32_e32 v84, 1.0, v84
	v_add_f32_e32 v85, 1.0, v85
	v_pk_fma_f32 v[94:95], v[94:95], v[98:99], v[96:97]
	v_lshlrev_b32_e32 v96, 16, v158
	v_and_b32_e32 v97, 0xffff0000, v158
	v_lshlrev_b32_e32 v98, 16, v154
	v_and_b32_e32 v99, 0xffff0000, v154
	v_rcp_f32_e32 v84, v84
	v_rcp_f32_e32 v85, v85
	v_add_f32_e32 v86, 1.0, v86
	v_add_f32_e32 v87, 1.0, v87
	v_pk_fma_f32 v[88:89], v[88:89], v[98:99], v[96:97]
	v_lshlrev_b32_e32 v96, 16, v159
	v_and_b32_e32 v97, 0xffff0000, v159
	v_lshlrev_b32_e32 v98, 16, v155
	v_and_b32_e32 v99, 0xffff0000, v155
	v_rcp_f32_e32 v86, v86
	v_rcp_f32_e32 v87, v87
	v_add_f32_e32 v80, 1.0, v80
	v_add_f32_e32 v81, 1.0, v81
	v_pk_fma_f32 v[90:91], v[90:91], v[98:99], v[96:97]
	v_lshl_add_u64 v[96:97], v[196:197], 2, s[2:3]
	v_rcp_f32_e32 v80, v80
	v_rcp_f32_e32 v81, v81
	flat_store_dwordx4 v[96:97], v[88:91] offset:16
	flat_store_dwordx4 v[96:97], v[92:95]
	v_mul_f32_e32 v82, v82, v100
	v_lshlrev_b32_e32 v88, 16, v148
	v_and_b32_e32 v89, 0xffff0000, v148
	v_lshlrev_b32_e32 v90, 16, v144
	v_and_b32_e32 v91, 0xffff0000, v144
	v_pk_fma_f32 v[84:85], v[84:85], v[90:91], v[88:89]
	v_lshlrev_b32_e32 v88, 16, v149
	v_and_b32_e32 v89, 0xffff0000, v149
	v_lshlrev_b32_e32 v90, 16, v145
	v_and_b32_e32 v91, 0xffff0000, v145
	v_pk_fma_f32 v[86:87], v[86:87], v[90:91], v[88:89]
	v_lshlrev_b32_e32 v88, 16, v150
	v_and_b32_e32 v89, 0xffff0000, v150
	v_lshlrev_b32_e32 v90, 16, v146
	v_and_b32_e32 v91, 0xffff0000, v146
	v_pk_fma_f32 v[80:81], v[80:81], v[90:91], v[88:89]
	v_fmamk_f32 v91, v191, 0x3a000000, v205
	v_mul_f32_e32 v92, 0x4b800000, v91
	v_cmp_gt_f32_e32 vcc, s40, v91
	flat_store_dwordx4 v[96:97], v[84:87] offset:128
	v_mul_f32_e32 v83, v83, v100
	v_cndmask_b32_e32 v91, v91, v92, vcc
	v_rsq_f32_e32 v92, v91
	v_exp_f32_e32 v82, v82
	v_exp_f32_e32 v83, v83
	v_lshlrev_b32_e32 v88, 16, v151
	v_mul_f32_e32 v84, 0x45800000, v92
	v_cndmask_b32_e32 v84, v92, v84, vcc
	v_mul_f32_e32 v84, 0xbfb8aa3b, v84
	v_mul_f32_e32 v76, v76, v84
	v_mul_f32_e32 v77, v77, v84
	v_exp_f32_e32 v76, v76
	v_exp_f32_e32 v77, v77
	v_mul_f32_e32 v78, v78, v84
	v_mul_f32_e32 v79, v79, v84
	v_exp_f32_e32 v78, v78
	v_exp_f32_e32 v79, v79
	v_mul_f32_e32 v72, v72, v84
	v_mul_f32_e32 v73, v73, v84
	v_add_f32_e32 v82, 1.0, v82
	v_add_f32_e32 v83, 1.0, v83
	v_exp_f32_e32 v72, v72
	v_exp_f32_e32 v73, v73
	v_mul_f32_e32 v74, v74, v84
	v_mul_f32_e32 v75, v75, v84
	v_rcp_f32_e32 v82, v82
	v_rcp_f32_e32 v83, v83
	v_exp_f32_e32 v74, v74
	v_exp_f32_e32 v75, v75
	v_add_f32_e32 v76, 1.0, v76
	v_add_f32_e32 v77, 1.0, v77
	v_mul_f32_e32 v68, v68, v84
	v_mul_f32_e32 v69, v69, v84
	v_rcp_f32_e32 v76, v76
	v_rcp_f32_e32 v77, v77
	v_add_f32_e32 v78, 1.0, v78
	v_add_f32_e32 v79, 1.0, v79
	v_exp_f32_e32 v68, v68
	v_exp_f32_e32 v69, v69
	v_mul_f32_e32 v70, v70, v84
	v_mul_f32_e32 v71, v71, v84
	v_and_b32_e32 v89, 0xffff0000, v151
	v_lshlrev_b32_e32 v90, 16, v147
	v_and_b32_e32 v91, 0xffff0000, v147
	v_rcp_f32_e32 v78, v78
	v_rcp_f32_e32 v79, v79
	v_add_f32_e32 v72, 1.0, v72
	v_add_f32_e32 v73, 1.0, v73
	v_exp_f32_e32 v70, v70
	v_exp_f32_e32 v71, v71
	v_mul_f32_e32 v64, v64, v84
	v_mul_f32_e32 v65, v65, v84
	v_pk_fma_f32 v[82:83], v[82:83], v[90:91], v[88:89]
	v_rcp_f32_e32 v72, v72
	v_rcp_f32_e32 v73, v73
	v_add_f32_e32 v74, 1.0, v74
	v_add_f32_e32 v75, 1.0, v75
	v_exp_f32_e32 v64, v64
	v_exp_f32_e32 v65, v65
	v_mul_f32_e32 v66, v66, v84
	v_mul_f32_e32 v67, v67, v84
	flat_store_dwordx4 v[96:97], v[80:83] offset:144
	v_rcp_f32_e32 v74, v74
	v_rcp_f32_e32 v75, v75
	v_lshlrev_b32_e32 v80, 16, v140
	v_and_b32_e32 v81, 0xffff0000, v140
	v_lshlrev_b32_e32 v82, 16, v136
	v_and_b32_e32 v83, 0xffff0000, v136
	v_exp_f32_e32 v66, v66
	v_exp_f32_e32 v67, v67
	v_pk_fma_f32 v[76:77], v[76:77], v[82:83], v[80:81]
	v_lshlrev_b32_e32 v80, 16, v141
	v_and_b32_e32 v81, 0xffff0000, v141
	v_lshlrev_b32_e32 v82, 16, v137
	v_and_b32_e32 v83, 0xffff0000, v137
	v_add_f32_e32 v68, 1.0, v68
	v_add_f32_e32 v69, 1.0, v69
	v_pk_fma_f32 v[78:79], v[78:79], v[82:83], v[80:81]
	v_lshlrev_b32_e32 v80, 16, v142
	v_and_b32_e32 v81, 0xffff0000, v142
	v_lshlrev_b32_e32 v82, 16, v138
	v_and_b32_e32 v83, 0xffff0000, v138
	v_rcp_f32_e32 v68, v68
	v_rcp_f32_e32 v69, v69
	v_add_f32_e32 v70, 1.0, v70
	v_add_f32_e32 v71, 1.0, v71
	v_pk_fma_f32 v[72:73], v[72:73], v[82:83], v[80:81]
; __device__ __forceinline__ float bflo(unsigned u) { return __uint_as_float(u << 16); }
;     __device__ __forceinline__ void operator()(const Acc& acc, const Unit& u, int wr, int wc, int fr, int fq) const {
;     ...
;             for (int m = 0; m < 4; ++m) { const int row = u.pm * 256 + ai * 128 + wr * 64 + m * 16 + fr; const size_t off = (size_t)row * DM + colbase;
;                 rsv[m] = rowss[row];
; #pragma unroll
;                 for (int bj = 0; bj < 2; ++bj) { const u32x4 hw = __builtin_nontemporal_load((const u32x4*)(hin + off + 32 * bj));
;                     hv[m][bj][0] = (f32x4){bflo(hw.x), bfhi(hw.x), bflo(hw.y), bfhi(hw.y)}; hv[m][bj][1] = (f32x4){bflo(hw.z), bfhi(hw.z), bflo(hw.w), bfhi(hw.w)};
;                     pw[m][bj] = __builtin_nontemporal_load((const u32x4*)(PP + off + 32 * bj)); } }
; #pragma unroll
;             for (int m = 0; m < 4; ++m) {
;                 const int row = u.pm * 256 + ai * 128 + wr * 64 + m * 16 + fr;
;                 const float rs = rsqrtf(rsv[m] * (1.0f / DM) + EPS) * -1.4426950408889634f;
; #pragma unroll
;                 for (int bj = 0; bj < 2; ++bj) {
;                     const size_t off = (size_t)row * DM + colbase + 32 * bj;
;                     f32x4 h0 = hv[m][bj][0], h1 = hv[m][bj][1];
;                     const u32x4 p4 = pw[m][bj];
;                     const f32x4 a0 = acc[ai][bj][m][0], a1 = acc[ai][bj][m][1];
;                     h0.x += bflo(p4.x) * __builtin_amdgcn_rcpf(1.0f + __builtin_amdgcn_exp2f(a0.x * rs));
;                     h0.y += bfhi(p4.x) * __builtin_amdgcn_rcpf(1.0f + __builtin_amdgcn_exp2f(a0.y * rs));
;                     h0.z += bflo(p4.y) * __builtin_amdgcn_rcpf(1.0f + __builtin_amdgcn_exp2f(a0.z * rs));
;                     h0.w += bfhi(p4.y) * __builtin_amdgcn_rcpf(1.0f + __builtin_amdgcn_exp2f(a0.w * rs));
;                     h1.x += bflo(p4.z) * __builtin_amdgcn_rcpf(1.0f + __builtin_amdgcn_exp2f(a1.x * rs));
;                     h1.y += bfhi(p4.z) * __builtin_amdgcn_rcpf(1.0f + __builtin_amdgcn_exp2f(a1.y * rs));
;                     h1.z += bflo(p4.w) * __builtin_amdgcn_rcpf(1.0f + __builtin_amdgcn_exp2f(a1.z * rs));
;                     h1.w += bfhi(p4.w) * __builtin_amdgcn_rcpf(1.0f + __builtin_amdgcn_exp2f(a1.w * rs));
;                     *(f32x4*)(out + off) = h0; *(f32x4*)(out + off + 4) = h1;
	v_lshlrev_b32_e32 v80, 16, v143
	v_and_b32_e32 v81, 0xffff0000, v143
	v_lshlrev_b32_e32 v82, 16, v139
	v_and_b32_e32 v83, 0xffff0000, v139
	v_rcp_f32_e32 v70, v70
	v_rcp_f32_e32 v71, v71
	v_add_f32_e32 v64, 1.0, v64
	v_add_f32_e32 v65, 1.0, v65
	v_pk_fma_f32 v[74:75], v[74:75], v[82:83], v[80:81]
	v_lshl_add_u64 v[80:81], v[194:195], 2, s[2:3]
	v_rcp_f32_e32 v64, v64
	v_rcp_f32_e32 v65, v65
	v_add_f32_e32 v66, 1.0, v66
	v_add_f32_e32 v67, 1.0, v67
	flat_store_dwordx4 v[80:81], v[72:75] offset:16
	v_rcp_f32_e32 v66, v66
	v_rcp_f32_e32 v67, v67
	v_lshlrev_b32_e32 v72, 16, v132
	v_and_b32_e32 v73, 0xffff0000, v132
	v_lshlrev_b32_e32 v74, 16, v128
	v_and_b32_e32 v75, 0xffff0000, v128
	v_pk_fma_f32 v[68:69], v[68:69], v[74:75], v[72:73]
	v_lshlrev_b32_e32 v72, 16, v133
	v_and_b32_e32 v73, 0xffff0000, v133
	v_lshlrev_b32_e32 v74, 16, v129
	v_and_b32_e32 v75, 0xffff0000, v129
	v_pk_fma_f32 v[70:71], v[70:71], v[74:75], v[72:73]
	v_lshlrev_b32_e32 v72, 16, v134
	v_and_b32_e32 v73, 0xffff0000, v134
	v_lshlrev_b32_e32 v74, 16, v130
	v_and_b32_e32 v75, 0xffff0000, v130
	v_pk_fma_f32 v[64:65], v[64:65], v[74:75], v[72:73]
	v_lshlrev_b32_e32 v72, 16, v135
	v_and_b32_e32 v73, 0xffff0000, v135
	v_lshlrev_b32_e32 v74, 16, v131
	v_and_b32_e32 v75, 0xffff0000, v131
	flat_store_dwordx4 v[80:81], v[76:79]
	v_pk_fma_f32 v[66:67], v[66:67], v[74:75], v[72:73]
	flat_store_dwordx4 v[80:81], v[68:71] offset:128
	flat_store_dwordx4 v[80:81], v[64:67] offset:144
	flat_load_dword v68, v[192:193] offset:512
	s_nop 0
	v_add_u32_e32 v64, 0x80, v190
	v_ashrrev_i32_e32 v65, 31, v64
	v_lshlrev_b64 v[64:65], 11, v[64:65]
	v_lshl_add_u64 v[136:137], v[64:65], 0, v[188:189]
	v_lshlrev_b64 v[64:65], 1, v[136:137]
	v_lshl_add_u64 v[66:67], s[6:7], 0, v[64:65]
	v_lshl_add_u64 v[64:65], s[8:9], 0, v[64:65]
	v_mov_b64_e32 v[124:125], v[248:249]
	v_mov_b64_e32 v[126:127], v[252:253]
	flat_load_dwordx4 v[128:131], v[64:65] nt
	v_mov_b64_e32 v[132:133], v[236:237]
	v_mov_b64_e32 v[134:135], v[238:239]
	flat_load_dwordx4 v[112:115], v[64:65] offset:64 nt
	v_add_u32_e32 v64, 0x90, v190
	v_ashrrev_i32_e32 v65, 31, v64
	v_lshlrev_b64 v[64:65], 11, v[64:65]
	v_lshl_add_u64 v[120:121], v[64:65], 0, v[188:189]
	v_lshlrev_b64 v[64:65], 1, v[120:121]
	v_lshl_add_u64 v[66:67], s[6:7], 0, v[64:65]
	v_lshl_add_u64 v[64:65], s[8:9], 0, v[64:65]
	v_mov_b64_e32 v[108:109], v[240:241]
	v_mov_b64_e32 v[110:111], v[250:251]
	v_mov_b32_e32 v100, 0x20000
	v_lshl_add_u32 v100, v200, 4, v100
	v_lshl_add_u32 v100, s79, 6, v100
	v_lshl_add_u32 v100, s86, 4, v100
	ds_read_b128 v[100:103], v100
	flat_load_dwordx4 v[104:107], v[64:65] nt
	flat_load_dwordx4 v[96:99], v[64:65] offset:64 nt
	v_add_u32_e32 v64, 0xa0, v190
	v_ashrrev_i32_e32 v65, 31, v64
	v_lshlrev_b64 v[64:65], 11, v[64:65]
	v_lshl_add_u64 v[118:119], v[64:65], 0, v[188:189]
	v_lshlrev_b64 v[64:65], 1, v[118:119]
	v_lshl_add_u64 v[66:67], s[6:7], 0, v[64:65]
	v_lshl_add_u64 v[64:65], s[8:9], 0, v[64:65]
	flat_load_dwordx4 v[92:95], v[66:67] nt
	flat_load_dwordx4 v[84:87], v[66:67] offset:64 nt
	flat_load_dwordx4 v[88:91], v[64:65] nt
	flat_load_dwordx4 v[80:83], v[64:65] offset:64 nt
	flat_load_dword v123, v[192:193] offset:576
	flat_load_dword v142, v[192:193] offset:640
	flat_load_dword v122, v[192:193] offset:704
	v_add_u32_e32 v64, 0xb0, v190
	v_ashrrev_i32_e32 v65, 31, v64
	v_lshlrev_b64 v[64:65], 11, v[64:65]
	v_lshl_add_u64 v[116:117], v[64:65], 0, v[188:189]
	v_lshlrev_b64 v[64:65], 1, v[116:117]
	v_lshl_add_u64 v[66:67], s[6:7], 0, v[64:65]
	s_waitcnt vmcnt(0) lgkmcnt(0)
	v_fmamk_f32 v68, v68, 0x3a000000, v205
	v_mul_f32_e32 v69, 0x4b800000, v68
	v_cmp_gt_f32_e32 vcc, s40, v68
	v_lshlrev_b32_e32 v140, 16, v128
	s_nop 0
	v_cndmask_b32_e32 v68, v68, v69, vcc
	v_rsq_f32_e32 v70, v68
	v_lshl_add_u64 v[68:69], s[8:9], 0, v[64:65]
	v_lshlrev_b32_e32 v138, 16, v124
	v_and_b32_e32 v139, 0xffff0000, v124
	v_mul_f32_e32 v71, 0x45800000, v70
	v_cndmask_b32_e32 v70, v70, v71, vcc
	v_mul_f32_e32 v143, 0xbfb8aa3b, v70
	v_mul_f32_e32 v62, v62, v143
	v_mul_f32_e32 v63, v63, v143
	v_exp_f32_e32 v62, v62
	v_exp_f32_e32 v63, v63
	v_mul_f32_e32 v56, v56, v143
	v_mul_f32_e32 v57, v57, v143
	v_exp_f32_e32 v56, v56
	v_exp_f32_e32 v57, v57
	v_mul_f32_e32 v58, v58, v143
	v_mul_f32_e32 v59, v59, v143
	v_exp_f32_e32 v58, v58
	v_exp_f32_e32 v59, v59
	v_mul_f32_e32 v52, v52, v143
	v_mul_f32_e32 v53, v53, v143
	v_add_f32_e32 v62, 1.0, v62
	v_add_f32_e32 v63, 1.0, v63
	v_exp_f32_e32 v52, v52
	v_exp_f32_e32 v53, v53
	v_mul_f32_e32 v54, v54, v143
	v_mul_f32_e32 v55, v55, v143
	v_mul_f32_e32 v60, v60, v143
	v_mul_f32_e32 v61, v61, v143
	v_rcp_f32_e32 v62, v62
	v_rcp_f32_e32 v63, v63
	v_add_f32_e32 v56, 1.0, v56
	v_add_f32_e32 v57, 1.0, v57
	v_exp_f32_e32 v54, v54
	v_exp_f32_e32 v55, v55
	v_mul_f32_e32 v48, v48, v143
	v_mul_f32_e32 v49, v49, v143
	v_exp_f32_e32 v60, v60
	v_exp_f32_e32 v61, v61
	v_rcp_f32_e32 v56, v56
	v_rcp_f32_e32 v57, v57
	v_add_f32_e32 v58, 1.0, v58
	v_add_f32_e32 v59, 1.0, v59
	v_exp_f32_e32 v48, v48
	v_exp_f32_e32 v49, v49
	v_rcp_f32_e32 v58, v58
	v_rcp_f32_e32 v59, v59
	v_and_b32_e32 v141, 0xffff0000, v128
	v_lshlrev_b32_e32 v124, 16, v125
	v_and_b32_e32 v125, 0xffff0000, v125
	v_lshlrev_b32_e32 v128, 16, v129
	v_and_b32_e32 v129, 0xffff0000, v129
	v_add_f32_e32 v52, 1.0, v52
	v_add_f32_e32 v53, 1.0, v53
	flat_load_dwordx4 v[72:75], v[66:67] nt
	s_nop 0
	flat_load_dwordx4 v[64:67], v[66:67] offset:64 nt
	s_nop 0
	flat_load_dwordx4 v[76:79], v[68:69] nt
	s_nop 0
	flat_load_dwordx4 v[68:71], v[68:69] offset:64 nt
	v_pk_fma_f32 v[62:63], v[62:63], v[128:129], v[124:125]
	v_lshlrev_b32_e32 v124, 16, v126
	v_and_b32_e32 v125, 0xffff0000, v126
; __device__ __forceinline__ float bflo(unsigned u) { return __uint_as_float(u << 16); }
; __device__ __forceinline__ float bfhi(unsigned u) { return __uint_as_float(u & 0xffff0000u); }
;     __device__ __forceinline__ void operator()(const Acc& acc, const Unit& u, int wr, int wc, int fr, int fq) const {
;     ...
;             for (int m = 0; m < 4; ++m) {
;                 const int row = u.pm * 256 + ai * 128 + wr * 64 + m * 16 + fr;
;                 const float rs = rsqrtf(rsv[m] * (1.0f / DM) + EPS) * -1.4426950408889634f;
; #pragma unroll
;                 for (int bj = 0; bj < 2; ++bj) {
;                     const size_t off = (size_t)row * DM + colbase + 32 * bj;
;                     f32x4 h0 = hv[m][bj][0], h1 = hv[m][bj][1];
;                     const u32x4 p4 = pw[m][bj];
;                     const f32x4 a0 = acc[ai][bj][m][0], a1 = acc[ai][bj][m][1];
;                     h0.x += bflo(p4.x) * __builtin_amdgcn_rcpf(1.0f + __builtin_amdgcn_exp2f(a0.x * rs));
;                     h0.y += bfhi(p4.x) * __builtin_amdgcn_rcpf(1.0f + __builtin_amdgcn_exp2f(a0.y * rs));
;                     h0.z += bflo(p4.y) * __builtin_amdgcn_rcpf(1.0f + __builtin_amdgcn_exp2f(a0.z * rs));
;                     h0.w += bfhi(p4.y) * __builtin_amdgcn_rcpf(1.0f + __builtin_amdgcn_exp2f(a0.w * rs));
;                     h1.x += bflo(p4.z) * __builtin_amdgcn_rcpf(1.0f + __builtin_amdgcn_exp2f(a1.x * rs));
;                     h1.y += bfhi(p4.z) * __builtin_amdgcn_rcpf(1.0f + __builtin_amdgcn_exp2f(a1.y * rs));
;                     h1.z += bflo(p4.w) * __builtin_amdgcn_rcpf(1.0f + __builtin_amdgcn_exp2f(a1.z * rs));
;                     h1.w += bfhi(p4.w) * __builtin_amdgcn_rcpf(1.0f + __builtin_amdgcn_exp2f(a1.w * rs));
;                     *(f32x4*)(out + off) = h0; *(f32x4*)(out + off + 4) = h1;
	v_lshlrev_b32_e32 v128, 16, v130
	v_and_b32_e32 v129, 0xffff0000, v130
	v_rcp_f32_e32 v52, v52
	v_rcp_f32_e32 v53, v53
	v_add_f32_e32 v54, 1.0, v54
	v_add_f32_e32 v55, 1.0, v55
	v_add_f32_e32 v60, 1.0, v60
	v_add_f32_e32 v61, 1.0, v61
	v_pk_fma_f32 v[56:57], v[56:57], v[128:129], v[124:125]
	v_lshlrev_b32_e32 v124, 16, v127
	v_and_b32_e32 v125, 0xffff0000, v127
	v_lshlrev_b32_e32 v126, 16, v131
	v_and_b32_e32 v127, 0xffff0000, v131
	v_rcp_f32_e32 v54, v54
	v_rcp_f32_e32 v55, v55
	v_add_f32_e32 v48, 1.0, v48
	v_add_f32_e32 v49, 1.0, v49
	v_rcp_f32_e32 v60, v60
	v_rcp_f32_e32 v61, v61
	v_pk_fma_f32 v[58:59], v[58:59], v[126:127], v[124:125]
	v_lshl_add_u64 v[124:125], v[136:137], 2, s[2:3]
	v_rcp_f32_e32 v48, v48
	v_rcp_f32_e32 v49, v49
	flat_store_dwordx4 v[124:125], v[56:59] offset:16
	v_pk_fma_f32 v[60:61], v[60:61], v[140:141], v[138:139]
	flat_store_dwordx4 v[124:125], v[60:63]
	v_lshlrev_b32_e32 v56, 16, v132
	v_and_b32_e32 v57, 0xffff0000, v132
	v_lshlrev_b32_e32 v58, 16, v112
	v_and_b32_e32 v59, 0xffff0000, v112
	v_pk_fma_f32 v[52:53], v[52:53], v[58:59], v[56:57]
	v_lshlrev_b32_e32 v56, 16, v133
	v_and_b32_e32 v57, 0xffff0000, v133
	v_lshlrev_b32_e32 v58, 16, v113
	v_and_b32_e32 v59, 0xffff0000, v113
	v_pk_fma_f32 v[54:55], v[54:55], v[58:59], v[56:57]
	v_lshlrev_b32_e32 v56, 16, v134
	v_and_b32_e32 v57, 0xffff0000, v134
	v_lshlrev_b32_e32 v58, 16, v114
	v_and_b32_e32 v59, 0xffff0000, v114
	v_pk_fma_f32 v[48:49], v[48:49], v[58:59], v[56:57]
	v_fmamk_f32 v59, v123, 0x3a000000, v205
	v_mul_f32_e32 v60, 0x4b800000, v59
	v_cmp_gt_f32_e32 vcc, s40, v59
	flat_store_dwordx4 v[124:125], v[52:55] offset:128
	v_mul_f32_e32 v50, v50, v143
	v_cndmask_b32_e32 v59, v59, v60, vcc
	v_rsq_f32_e32 v60, v59
	v_mul_f32_e32 v51, v51, v143
	v_exp_f32_e32 v50, v50
	v_exp_f32_e32 v51, v51
	v_mul_f32_e32 v52, 0x45800000, v60
	v_cndmask_b32_e32 v52, v60, v52, vcc
	v_mul_f32_e32 v52, 0xbfb8aa3b, v52
	v_mul_f32_e32 v44, v44, v52
	v_mul_f32_e32 v45, v45, v52
	v_exp_f32_e32 v44, v44
	v_exp_f32_e32 v45, v45
	v_mul_f32_e32 v46, v46, v52
	v_mul_f32_e32 v47, v47, v52
	v_exp_f32_e32 v46, v46
	v_exp_f32_e32 v47, v47
	v_mul_f32_e32 v40, v40, v52
	v_mul_f32_e32 v41, v41, v52
	v_add_f32_e32 v50, 1.0, v50
	v_add_f32_e32 v51, 1.0, v51
	v_exp_f32_e32 v40, v40
	v_exp_f32_e32 v41, v41
	v_mul_f32_e32 v42, v42, v52
	v_mul_f32_e32 v43, v43, v52
	v_rcp_f32_e32 v50, v50
	v_rcp_f32_e32 v51, v51
	v_exp_f32_e32 v42, v42
	v_exp_f32_e32 v43, v43
	v_add_f32_e32 v44, 1.0, v44
	v_add_f32_e32 v45, 1.0, v45
	v_mul_f32_e32 v36, v36, v52
	v_mul_f32_e32 v37, v37, v52
	v_rcp_f32_e32 v44, v44
	v_rcp_f32_e32 v45, v45
	v_add_f32_e32 v46, 1.0, v46
	v_add_f32_e32 v47, 1.0, v47
	v_exp_f32_e32 v36, v36
	v_exp_f32_e32 v37, v37
	v_mul_f32_e32 v38, v38, v52
	v_mul_f32_e32 v39, v39, v52
	v_lshlrev_b32_e32 v56, 16, v135
	v_and_b32_e32 v57, 0xffff0000, v135
	v_lshlrev_b32_e32 v58, 16, v115
	v_and_b32_e32 v59, 0xffff0000, v115
	v_rcp_f32_e32 v46, v46
	v_rcp_f32_e32 v47, v47
	v_add_f32_e32 v40, 1.0, v40
	v_add_f32_e32 v41, 1.0, v41
	v_exp_f32_e32 v38, v38
	v_exp_f32_e32 v39, v39
	v_mul_f32_e32 v32, v32, v52
	v_mul_f32_e32 v33, v33, v52
	v_pk_fma_f32 v[50:51], v[50:51], v[58:59], v[56:57]
	v_rcp_f32_e32 v40, v40
	v_rcp_f32_e32 v41, v41
	v_add_f32_e32 v42, 1.0, v42
	v_add_f32_e32 v43, 1.0, v43
	v_exp_f32_e32 v32, v32
	v_exp_f32_e32 v33, v33
	flat_store_dwordx4 v[124:125], v[48:51] offset:144
	v_rcp_f32_e32 v42, v42
	v_rcp_f32_e32 v43, v43
	v_lshlrev_b32_e32 v48, 16, v108
	v_and_b32_e32 v49, 0xffff0000, v108
	v_lshlrev_b32_e32 v50, 16, v104
	v_and_b32_e32 v51, 0xffff0000, v104
	v_pk_fma_f32 v[44:45], v[44:45], v[50:51], v[48:49]
	v_lshlrev_b32_e32 v48, 16, v109
	v_and_b32_e32 v49, 0xffff0000, v109
	v_lshlrev_b32_e32 v50, 16, v105
	v_and_b32_e32 v51, 0xffff0000, v105
	v_add_f32_e32 v36, 1.0, v36
	v_add_f32_e32 v37, 1.0, v37
	v_pk_fma_f32 v[46:47], v[46:47], v[50:51], v[48:49]
	v_lshlrev_b32_e32 v48, 16, v110
	v_and_b32_e32 v49, 0xffff0000, v110
	v_lshlrev_b32_e32 v50, 16, v106
	v_and_b32_e32 v51, 0xffff0000, v106
	v_rcp_f32_e32 v36, v36
	v_rcp_f32_e32 v37, v37
	v_add_f32_e32 v38, 1.0, v38
	v_add_f32_e32 v39, 1.0, v39
	v_pk_fma_f32 v[40:41], v[40:41], v[50:51], v[48:49]
	v_lshlrev_b32_e32 v48, 16, v111
	v_and_b32_e32 v49, 0xffff0000, v111
	v_lshlrev_b32_e32 v50, 16, v107
	v_and_b32_e32 v51, 0xffff0000, v107
	v_rcp_f32_e32 v38, v38
	v_rcp_f32_e32 v39, v39
	v_add_f32_e32 v32, 1.0, v32
	v_add_f32_e32 v33, 1.0, v33
	v_pk_fma_f32 v[42:43], v[42:43], v[50:51], v[48:49]
	v_lshl_add_u64 v[48:49], v[120:121], 2, s[2:3]
	v_rcp_f32_e32 v32, v32
	v_rcp_f32_e32 v33, v33
	flat_store_dwordx4 v[48:49], v[40:43] offset:16
	flat_store_dwordx4 v[48:49], v[44:47]
	v_mul_f32_e32 v34, v34, v52
	v_lshlrev_b32_e32 v40, 16, v100
	v_and_b32_e32 v41, 0xffff0000, v100
	v_lshlrev_b32_e32 v42, 16, v96
	v_and_b32_e32 v43, 0xffff0000, v96
	v_pk_fma_f32 v[36:37], v[36:37], v[42:43], v[40:41]
	v_lshlrev_b32_e32 v40, 16, v101
	v_and_b32_e32 v41, 0xffff0000, v101
	v_lshlrev_b32_e32 v42, 16, v97
	v_and_b32_e32 v43, 0xffff0000, v97
	v_pk_fma_f32 v[38:39], v[38:39], v[42:43], v[40:41]
	v_lshlrev_b32_e32 v40, 16, v102
	v_and_b32_e32 v41, 0xffff0000, v102
	v_lshlrev_b32_e32 v42, 16, v98
	v_and_b32_e32 v43, 0xffff0000, v98
	v_pk_fma_f32 v[32:33], v[32:33], v[42:43], v[40:41]
	v_fmamk_f32 v43, v142, 0x3a000000, v205
	v_mul_f32_e32 v44, 0x4b800000, v43
	v_cmp_gt_f32_e32 vcc, s40, v43
	flat_store_dwordx4 v[48:49], v[36:39] offset:128
	v_mul_f32_e32 v35, v35, v52
	v_cndmask_b32_e32 v43, v43, v44, vcc
	v_rsq_f32_e32 v44, v43
	v_exp_f32_e32 v34, v34
	v_exp_f32_e32 v35, v35
	v_lshlrev_b32_e32 v40, 16, v103
	v_mul_f32_e32 v36, 0x45800000, v44
; __device__ __forceinline__ float bflo(unsigned u) { return __uint_as_float(u << 16); }
; __device__ __forceinline__ float bfhi(unsigned u) { return __uint_as_float(u & 0xffff0000u); }
;     __device__ __forceinline__ void operator()(const Acc& acc, const Unit& u, int wr, int wc, int fr, int fq) const {
;     ...
;             for (int m = 0; m < 4; ++m) {
;                 const int row = u.pm * 256 + ai * 128 + wr * 64 + m * 16 + fr;
;                 const float rs = rsqrtf(rsv[m] * (1.0f / DM) + EPS) * -1.4426950408889634f;
; #pragma unroll
;                 for (int bj = 0; bj < 2; ++bj) {
;                     const size_t off = (size_t)row * DM + colbase + 32 * bj;
;                     f32x4 h0 = hv[m][bj][0], h1 = hv[m][bj][1];
;                     const u32x4 p4 = pw[m][bj];
;                     const f32x4 a0 = acc[ai][bj][m][0], a1 = acc[ai][bj][m][1];
;                     h0.x += bflo(p4.x) * __builtin_amdgcn_rcpf(1.0f + __builtin_amdgcn_exp2f(a0.x * rs));
;                     h0.y += bfhi(p4.x) * __builtin_amdgcn_rcpf(1.0f + __builtin_amdgcn_exp2f(a0.y * rs));
;                     h0.z += bflo(p4.y) * __builtin_amdgcn_rcpf(1.0f + __builtin_amdgcn_exp2f(a0.z * rs));
;                     h0.w += bfhi(p4.y) * __builtin_amdgcn_rcpf(1.0f + __builtin_amdgcn_exp2f(a0.w * rs));
;                     h1.x += bflo(p4.z) * __builtin_amdgcn_rcpf(1.0f + __builtin_amdgcn_exp2f(a1.x * rs));
;                     h1.y += bfhi(p4.z) * __builtin_amdgcn_rcpf(1.0f + __builtin_amdgcn_exp2f(a1.y * rs));
;                     h1.z += bflo(p4.w) * __builtin_amdgcn_rcpf(1.0f + __builtin_amdgcn_exp2f(a1.z * rs));
;                     h1.w += bfhi(p4.w) * __builtin_amdgcn_rcpf(1.0f + __builtin_amdgcn_exp2f(a1.w * rs));
;                     *(f32x4*)(out + off) = h0; *(f32x4*)(out + off + 4) = h1;
	v_cndmask_b32_e32 v36, v44, v36, vcc
	v_mul_f32_e32 v36, 0xbfb8aa3b, v36
	v_mul_f32_e32 v28, v28, v36
	v_mul_f32_e32 v29, v29, v36
	v_exp_f32_e32 v28, v28
	v_exp_f32_e32 v29, v29
	v_mul_f32_e32 v30, v30, v36
	v_mul_f32_e32 v31, v31, v36
	v_exp_f32_e32 v30, v30
	v_exp_f32_e32 v31, v31
	v_mul_f32_e32 v24, v24, v36
	v_mul_f32_e32 v25, v25, v36
	v_add_f32_e32 v34, 1.0, v34
	v_add_f32_e32 v35, 1.0, v35
	v_exp_f32_e32 v24, v24
	v_exp_f32_e32 v25, v25
	v_mul_f32_e32 v26, v26, v36
	v_mul_f32_e32 v27, v27, v36
	v_rcp_f32_e32 v34, v34
	v_rcp_f32_e32 v35, v35
	v_exp_f32_e32 v26, v26
	v_exp_f32_e32 v27, v27
	v_add_f32_e32 v28, 1.0, v28
	v_add_f32_e32 v29, 1.0, v29
	v_mul_f32_e32 v20, v20, v36
	v_mul_f32_e32 v21, v21, v36
	v_rcp_f32_e32 v28, v28
	v_rcp_f32_e32 v29, v29
	v_add_f32_e32 v30, 1.0, v30
	v_add_f32_e32 v31, 1.0, v31
	v_exp_f32_e32 v20, v20
	v_exp_f32_e32 v21, v21
	v_mul_f32_e32 v22, v22, v36
	v_mul_f32_e32 v23, v23, v36
	v_and_b32_e32 v41, 0xffff0000, v103
	v_lshlrev_b32_e32 v42, 16, v99
	v_and_b32_e32 v43, 0xffff0000, v99
	v_rcp_f32_e32 v30, v30
	v_rcp_f32_e32 v31, v31
	v_add_f32_e32 v24, 1.0, v24
	v_add_f32_e32 v25, 1.0, v25
	v_exp_f32_e32 v22, v22
	v_exp_f32_e32 v23, v23
	v_mul_f32_e32 v16, v16, v36
	v_mul_f32_e32 v17, v17, v36
	v_pk_fma_f32 v[34:35], v[34:35], v[42:43], v[40:41]
	v_rcp_f32_e32 v24, v24
	v_rcp_f32_e32 v25, v25
	v_add_f32_e32 v26, 1.0, v26
	v_add_f32_e32 v27, 1.0, v27
	v_exp_f32_e32 v16, v16
	v_exp_f32_e32 v17, v17
	flat_store_dwordx4 v[48:49], v[32:35] offset:144
	v_rcp_f32_e32 v26, v26
	v_rcp_f32_e32 v27, v27
	v_lshlrev_b32_e32 v32, 16, v92
	v_and_b32_e32 v33, 0xffff0000, v92
	v_lshlrev_b32_e32 v34, 16, v88
	v_and_b32_e32 v35, 0xffff0000, v88
	v_pk_fma_f32 v[28:29], v[28:29], v[34:35], v[32:33]
	v_lshlrev_b32_e32 v32, 16, v93
	v_and_b32_e32 v33, 0xffff0000, v93
	v_lshlrev_b32_e32 v34, 16, v89
	v_and_b32_e32 v35, 0xffff0000, v89
	v_add_f32_e32 v20, 1.0, v20
	v_add_f32_e32 v21, 1.0, v21
	v_pk_fma_f32 v[30:31], v[30:31], v[34:35], v[32:33]
	v_lshlrev_b32_e32 v32, 16, v94
	v_and_b32_e32 v33, 0xffff0000, v94
	v_lshlrev_b32_e32 v34, 16, v90
	v_and_b32_e32 v35, 0xffff0000, v90
	v_rcp_f32_e32 v20, v20
	v_rcp_f32_e32 v21, v21
	v_add_f32_e32 v22, 1.0, v22
	v_add_f32_e32 v23, 1.0, v23
	v_pk_fma_f32 v[24:25], v[24:25], v[34:35], v[32:33]
	v_lshlrev_b32_e32 v32, 16, v95
	v_and_b32_e32 v33, 0xffff0000, v95
	v_lshlrev_b32_e32 v34, 16, v91
	v_and_b32_e32 v35, 0xffff0000, v91
	v_rcp_f32_e32 v22, v22
	v_rcp_f32_e32 v23, v23
	v_add_f32_e32 v16, 1.0, v16
	v_add_f32_e32 v17, 1.0, v17
	v_pk_fma_f32 v[26:27], v[26:27], v[34:35], v[32:33]
	v_lshl_add_u64 v[32:33], v[118:119], 2, s[2:3]
	v_rcp_f32_e32 v16, v16
	v_rcp_f32_e32 v17, v17
	flat_store_dwordx4 v[32:33], v[24:27] offset:16
	flat_store_dwordx4 v[32:33], v[28:31]
	v_mul_f32_e32 v18, v18, v36
	v_lshlrev_b32_e32 v24, 16, v84
	v_and_b32_e32 v25, 0xffff0000, v84
	v_lshlrev_b32_e32 v26, 16, v80
	v_and_b32_e32 v27, 0xffff0000, v80
	v_pk_fma_f32 v[20:21], v[20:21], v[26:27], v[24:25]
	v_lshlrev_b32_e32 v24, 16, v85
	v_and_b32_e32 v25, 0xffff0000, v85
	v_lshlrev_b32_e32 v26, 16, v81
	v_and_b32_e32 v27, 0xffff0000, v81
	v_pk_fma_f32 v[22:23], v[22:23], v[26:27], v[24:25]
	v_lshlrev_b32_e32 v24, 16, v86
	v_and_b32_e32 v25, 0xffff0000, v86
	v_lshlrev_b32_e32 v26, 16, v82
	v_and_b32_e32 v27, 0xffff0000, v82
	v_pk_fma_f32 v[16:17], v[16:17], v[26:27], v[24:25]
	v_fmamk_f32 v27, v122, 0x3a000000, v205
	v_mul_f32_e32 v28, 0x4b800000, v27
	v_cmp_gt_f32_e32 vcc, s40, v27
	flat_store_dwordx4 v[32:33], v[20:23] offset:128
	v_mul_f32_e32 v19, v19, v36
	v_cndmask_b32_e32 v27, v27, v28, vcc
	v_rsq_f32_e32 v28, v27
	v_exp_f32_e32 v18, v18
	v_exp_f32_e32 v19, v19
	v_lshlrev_b32_e32 v24, 16, v87
	v_mul_f32_e32 v20, 0x45800000, v28
	v_cndmask_b32_e32 v20, v28, v20, vcc
	v_mul_f32_e32 v20, 0xbfb8aa3b, v20
	v_mul_f32_e32 v12, v12, v20
	v_mul_f32_e32 v13, v13, v20
	v_exp_f32_e32 v12, v12
	v_exp_f32_e32 v13, v13
	v_mul_f32_e32 v14, v14, v20
	v_mul_f32_e32 v15, v15, v20
	v_exp_f32_e32 v14, v14
	v_exp_f32_e32 v15, v15
	v_mul_f32_e32 v8, v8, v20
	v_mul_f32_e32 v9, v9, v20
	v_add_f32_e32 v18, 1.0, v18
	v_add_f32_e32 v19, 1.0, v19
	v_exp_f32_e32 v8, v8
	v_exp_f32_e32 v9, v9
	v_mul_f32_e32 v10, v10, v20
	v_mul_f32_e32 v11, v11, v20
	v_rcp_f32_e32 v18, v18
	v_rcp_f32_e32 v19, v19
	v_exp_f32_e32 v10, v10
	v_exp_f32_e32 v11, v11
	v_add_f32_e32 v12, 1.0, v12
	v_add_f32_e32 v13, 1.0, v13
	v_mul_f32_e32 v4, v4, v20
	v_mul_f32_e32 v5, v5, v20
	v_rcp_f32_e32 v12, v12
	v_rcp_f32_e32 v13, v13
	v_add_f32_e32 v14, 1.0, v14
	v_add_f32_e32 v15, 1.0, v15
	v_exp_f32_e32 v4, v4
	v_exp_f32_e32 v5, v5
	v_mul_f32_e32 v6, v6, v20
	v_mul_f32_e32 v7, v7, v20
	v_and_b32_e32 v25, 0xffff0000, v87
	v_lshlrev_b32_e32 v26, 16, v83
	v_and_b32_e32 v27, 0xffff0000, v83
	v_rcp_f32_e32 v14, v14
	v_rcp_f32_e32 v15, v15
	v_add_f32_e32 v8, 1.0, v8
	v_add_f32_e32 v9, 1.0, v9
	v_exp_f32_e32 v6, v6
	v_exp_f32_e32 v7, v7
	v_mul_f32_e32 v0, v0, v20
	v_mul_f32_e32 v1, v1, v20
	v_pk_fma_f32 v[18:19], v[18:19], v[26:27], v[24:25]
	v_rcp_f32_e32 v8, v8
	v_rcp_f32_e32 v9, v9
	v_add_f32_e32 v10, 1.0, v10
	v_add_f32_e32 v11, 1.0, v11
	v_exp_f32_e32 v0, v0
	v_exp_f32_e32 v1, v1
	v_mul_f32_e32 v2, v2, v20
	v_mul_f32_e32 v3, v3, v20
	flat_store_dwordx4 v[32:33], v[16:19] offset:144
	v_rcp_f32_e32 v10, v10
	v_rcp_f32_e32 v11, v11
	s_waitcnt vmcnt(0) lgkmcnt(0)
; __device__ __forceinline__ float bflo(unsigned u) { return __uint_as_float(u << 16); }
; #define PG8_BAR __builtin_amdgcn_s_barrier()
; template <class Epi, bool ALIGN_EPI>
; __device__ __forceinline__ void gemm_phase(LAS unsigned char* lds, const Gemm g, const StaticOrder& S, const Epi& E, const int wid) {
;     ...
;         if (!has_next) break;
; #pragma unroll
;         for (int a = 0; a < 2; ++a)
; #pragma unroll
;             for (int b = 0; b < 2; ++b)
; #pragma unroll
;                 for (int m = 0; m < 4; ++m)
; #pragma unroll
;                     for (int n = 0; n < 2; ++n) acc[a][b][m][n] = (f32x4){0.f, 0.f, 0.f, 0.f};
;         cur = nxt; cA = nA; cB = nB; ++ui;
;         if constexpr (ALIGN_EPI) { if (wr == 1) PG8_BAR; }
;     __device__ __forceinline__ void operator()(const Acc& acc, const Unit& u, int wr, int wc, int fr, int fq) const {
;     ...
;             for (int m = 0; m < 4; ++m) {
;                 const int row = u.pm * 256 + ai * 128 + wr * 64 + m * 16 + fr;
;                 const float rs = rsqrtf(rsv[m] * (1.0f / DM) + EPS) * -1.4426950408889634f;
; #pragma unroll
;                 for (int bj = 0; bj < 2; ++bj) {
;                     const size_t off = (size_t)row * DM + colbase + 32 * bj;
;                     f32x4 h0 = hv[m][bj][0], h1 = hv[m][bj][1];
;                     const u32x4 p4 = pw[m][bj];
;                     const f32x4 a0 = acc[ai][bj][m][0], a1 = acc[ai][bj][m][1];
;                     h0.x += bflo(p4.x) * __builtin_amdgcn_rcpf(1.0f + __builtin_amdgcn_exp2f(a0.x * rs));
;                     h0.y += bfhi(p4.x) * __builtin_amdgcn_rcpf(1.0f + __builtin_amdgcn_exp2f(a0.y * rs));
;                     h0.z += bflo(p4.y) * __builtin_amdgcn_rcpf(1.0f + __builtin_amdgcn_exp2f(a0.z * rs));
;                     h0.w += bfhi(p4.y) * __builtin_amdgcn_rcpf(1.0f + __builtin_amdgcn_exp2f(a0.w * rs));
;                     h1.x += bflo(p4.z) * __builtin_amdgcn_rcpf(1.0f + __builtin_amdgcn_exp2f(a1.x * rs));
;                     h1.y += bfhi(p4.z) * __builtin_amdgcn_rcpf(1.0f + __builtin_amdgcn_exp2f(a1.y * rs));
;                     h1.z += bflo(p4.w) * __builtin_amdgcn_rcpf(1.0f + __builtin_amdgcn_exp2f(a1.z * rs));
;                     h1.w += bfhi(p4.w) * __builtin_amdgcn_rcpf(1.0f + __builtin_amdgcn_exp2f(a1.w * rs));
;                     *(f32x4*)(out + off) = h0; *(f32x4*)(out + off + 4) = h1;
	v_lshlrev_b32_e32 v16, 16, v72
	v_and_b32_e32 v17, 0xffff0000, v72
	v_lshlrev_b32_e32 v18, 16, v76
	v_and_b32_e32 v19, 0xffff0000, v76
	v_exp_f32_e32 v2, v2
	v_exp_f32_e32 v3, v3
	v_pk_fma_f32 v[12:13], v[12:13], v[18:19], v[16:17]
	v_lshlrev_b32_e32 v16, 16, v73
	v_and_b32_e32 v17, 0xffff0000, v73
	v_lshlrev_b32_e32 v18, 16, v77
	v_and_b32_e32 v19, 0xffff0000, v77
	v_add_f32_e32 v4, 1.0, v4
	v_add_f32_e32 v5, 1.0, v5
	v_pk_fma_f32 v[14:15], v[14:15], v[18:19], v[16:17]
	v_lshlrev_b32_e32 v16, 16, v74
	v_and_b32_e32 v17, 0xffff0000, v74
	v_lshlrev_b32_e32 v18, 16, v78
	v_and_b32_e32 v19, 0xffff0000, v78
	v_rcp_f32_e32 v4, v4
	v_rcp_f32_e32 v5, v5
	v_add_f32_e32 v6, 1.0, v6
	v_add_f32_e32 v7, 1.0, v7
	v_pk_fma_f32 v[8:9], v[8:9], v[18:19], v[16:17]
	v_lshlrev_b32_e32 v16, 16, v75
	v_and_b32_e32 v17, 0xffff0000, v75
	v_lshlrev_b32_e32 v18, 16, v79
	v_and_b32_e32 v19, 0xffff0000, v79
	v_rcp_f32_e32 v6, v6
	v_rcp_f32_e32 v7, v7
	v_add_f32_e32 v0, 1.0, v0
	v_add_f32_e32 v1, 1.0, v1
	v_pk_fma_f32 v[10:11], v[10:11], v[18:19], v[16:17]
	v_lshl_add_u64 v[16:17], v[116:117], 2, s[2:3]
	v_rcp_f32_e32 v0, v0
	v_rcp_f32_e32 v1, v1
	v_add_f32_e32 v2, 1.0, v2
	v_add_f32_e32 v3, 1.0, v3
	flat_store_dwordx4 v[16:17], v[8:11] offset:16
	v_rcp_f32_e32 v2, v2
	v_rcp_f32_e32 v3, v3
	v_lshlrev_b32_e32 v8, 16, v64
	v_and_b32_e32 v9, 0xffff0000, v64
	v_lshlrev_b32_e32 v10, 16, v68
	v_and_b32_e32 v11, 0xffff0000, v68
	v_pk_fma_f32 v[4:5], v[4:5], v[10:11], v[8:9]
	v_lshlrev_b32_e32 v8, 16, v65
	v_and_b32_e32 v9, 0xffff0000, v65
	v_lshlrev_b32_e32 v10, 16, v69
	v_and_b32_e32 v11, 0xffff0000, v69
	v_pk_fma_f32 v[6:7], v[6:7], v[10:11], v[8:9]
	v_lshlrev_b32_e32 v8, 16, v66
	v_and_b32_e32 v9, 0xffff0000, v66
	v_lshlrev_b32_e32 v10, 16, v70
	v_and_b32_e32 v11, 0xffff0000, v70
	v_pk_fma_f32 v[0:1], v[0:1], v[10:11], v[8:9]
	v_lshlrev_b32_e32 v8, 16, v67
	v_and_b32_e32 v9, 0xffff0000, v67
	v_lshlrev_b32_e32 v10, 16, v71
	v_and_b32_e32 v11, 0xffff0000, v71
	s_andn2_b64 vcc, exec, s[4:5]
	s_mov_b64 s[4:5], -1
	flat_store_dwordx4 v[16:17], v[12:15]
	v_pk_fma_f32 v[2:3], v[2:3], v[10:11], v[8:9]
	flat_store_dwordx4 v[16:17], v[4:7] offset:128
	flat_store_dwordx4 v[16:17], v[0:3] offset:144
	s_cbranch_vccnz .LBB0_803
	s_and_b64 vcc, exec, s[0:1]
	s_cbranch_vccnz .LBB0_802
	s_barrier
	s_branch .LBB0_802
